# attention epilogue: z-gate pieces fetched as eight 16-byte loads per lane and redistributed with v_permlane32_swap instead of sixteen 8-byte loads
# speedup vs baseline: 1.0253x; 1.0086x over previous
.LBB0_737:
	v_mov_b32_e32 v130, v210
	s_add_i32 s74, s74, 1
	v_ashrrev_i32_e32 v189, 31, v188
	v_lshl_add_u64 v[128:129], v[188:189], 0, s[46:47]
	v_lshlrev_b32_e32 v130, 2, v130
	v_lshlrev_b64 v[140:141], 11, v[128:129]
	v_lshl_or_b32 v140, s75, 1, v140
	v_ashrrev_i32_e32 v131, 31, v130
	v_lshl_add_u64 v[128:129], s[48:49], 0, v[140:141]
	v_lshlrev_b64 v[136:137], 1, v[130:131]
	v_lshl_add_u64 v[134:135], v[136:137], 1, v[128:129]
	v_lshlrev_b32_e32 v215, 3, v206
	global_load_dwordx2 v[138:139], v215, s[52:53]
	global_load_dwordx4 v[160:163], v[134:135], off
	global_load_dwordx4 v[164:167], v[134:135], off offset:32
	global_load_dwordx4 v[168:171], v[134:135], off offset:64
	global_load_dwordx4 v[172:175], v[134:135], off offset:96
	global_load_dwordx4 v[202:205], v[134:135], off offset:128
	global_load_dwordx4 v[244:247], v[134:135], off offset:160
	global_load_dwordx4 v[248:251], v[134:135], off offset:192
	global_load_dwordx4 v[252:255], v[134:135], off offset:224
	s_lshr_b32 s0, s87, 2
	s_add_i32 s0, s0, 0x8000
	v_add_u32_e32 v217, s0, v215
	v_lshl_add_u32 v219, v210, 4, s0
	s_waitcnt lgkmcnt(0)
	s_barrier
	s_waitcnt vmcnt(8)
	ds_write_b64 v217, v[138:139]
	s_lshr_b32 s0, s100, 30
	s_add_i32 s0, s0, 3
	s_cmp_lt_u32 s74, s0
	s_cbranch_scc1 .Lpf_do
	s_waitcnt vmcnt(0)
	s_branch .Lpf_done

.Lpf_done:
	v_mov_b32_e32 v128, v197
	v_mov_b32_e32 v129, v196
	s_nop 0
	v_permlane32_swap_b32_e32 v197, v128
	v_permlane32_swap_b32_e32 v196, v129
	v_add_f32_e32 v148, v197, v128
	v_add_f32_e32 v149, v196, v129
	v_div_scale_f32 v150, s[0:1], v148, v148, 1.0
	v_div_scale_f32 v152, s[0:1], v149, v149, -v208
	v_rcp_f32_e32 v154, v150
	v_rcp_f32_e32 v155, v152
	v_div_scale_f32 v151, vcc, 1.0, v148, 1.0
	v_fma_f32 v156, -v150, v154, 1.0
	v_fma_f32 v157, -v152, v155, 1.0
	v_fmac_f32_e32 v154, v156, v154
	v_div_scale_f32 v153, s[36:37], -v208, v149, -v208
	v_fmac_f32_e32 v155, v157, v155
	v_mul_f32_e32 v156, v151, v154
	v_mul_f32_e32 v157, v153, v155
	v_fma_f32 v158, -v150, v156, v151
	v_fma_f32 v159, -v152, v157, v153
	v_fmac_f32_e32 v156, v158, v154
	v_fmac_f32_e32 v157, v159, v155
	v_fma_f32 v150, -v150, v156, v151
	v_fma_f32 v151, -v152, v157, v153
	v_div_fmas_f32 v150, v150, v154, v156
	s_mov_b64 vcc, s[36:37]
	v_div_fixup_f32 v148, v150, v148, 1.0
	v_div_fmas_f32 v150, v151, v155, v157
	v_div_fixup_f32 v150, v150, v149, -v208
	v_pk_mul_f32 v[96:97], v[96:97], v[150:151] op_sel_hi:[1,0]
	v_pk_mul_f32 v[98:99], v[98:99], v[150:151] op_sel_hi:[1,0]
	v_pk_fma_f32 v[112:113], v[112:113], v[148:149], v[96:97] op_sel_hi:[1,0,1]
	v_pk_fma_f32 v[114:115], v[114:115], v[148:149], v[98:99] op_sel_hi:[1,0,1]
	v_mul_f32_e32 v96, v113, v113
	v_pk_fma_f32 v[96:97], v[112:113], v[112:113], v[96:97] op_sel_hi:[1,1,0]
	v_pk_mul_f32 v[100:101], v[100:101], v[150:151] op_sel_hi:[1,0]
	v_mul_f32_e32 v98, v115, v115
	v_pk_fma_f32 v[96:97], v[114:115], v[114:115], v[96:97]
	v_pk_fma_f32 v[100:101], v[116:117], v[148:149], v[100:101] op_sel_hi:[1,0,1]
	v_pk_add_f32 v[96:97], v[98:99], v[96:97] op_sel_hi:[0,1]
	v_pk_mul_f32 v[102:103], v[102:103], v[150:151] op_sel_hi:[1,0]
	v_mul_f32_e32 v116, v101, v101
	v_pk_fma_f32 v[96:97], v[100:101], v[100:101], v[96:97]
	v_pk_fma_f32 v[102:103], v[118:119], v[148:149], v[102:103] op_sel_hi:[1,0,1]
	v_pk_add_f32 v[96:97], v[116:117], v[96:97] op_sel_hi:[0,1]
	v_pk_mul_f32 v[104:105], v[104:105], v[150:151] op_sel_hi:[1,0]
	v_mul_f32_e32 v118, v103, v103
	v_pk_fma_f32 v[96:97], v[102:103], v[102:103], v[96:97]
	v_pk_fma_f32 v[104:105], v[120:121], v[148:149], v[104:105] op_sel_hi:[1,0,1]
	v_pk_add_f32 v[96:97], v[118:119], v[96:97] op_sel_hi:[0,1]
	v_pk_mul_f32 v[106:107], v[106:107], v[150:151] op_sel_hi:[1,0]
	v_mul_f32_e32 v120, v105, v105
	v_pk_fma_f32 v[96:97], v[104:105], v[104:105], v[96:97]
	v_pk_fma_f32 v[106:107], v[122:123], v[148:149], v[106:107] op_sel_hi:[1,0,1]
	v_pk_add_f32 v[96:97], v[120:121], v[96:97] op_sel_hi:[0,1]
	v_pk_mul_f32 v[108:109], v[108:109], v[150:151] op_sel_hi:[1,0]
	v_mul_f32_e32 v122, v107, v107
	v_pk_fma_f32 v[96:97], v[106:107], v[106:107], v[96:97]
	v_pk_fma_f32 v[108:109], v[124:125], v[148:149], v[108:109] op_sel_hi:[1,0,1]
	v_pk_add_f32 v[96:97], v[122:123], v[96:97] op_sel_hi:[0,1]
	v_pk_mul_f32 v[110:111], v[110:111], v[150:151] op_sel_hi:[1,0]
	v_pk_fma_f32 v[96:97], v[108:109], v[108:109], v[96:97]
	v_mul_f32_e32 v98, v109, v109
	v_pk_fma_f32 v[110:111], v[126:127], v[148:149], v[110:111] op_sel_hi:[1,0,1]
	v_pk_add_f32 v[96:97], v[98:99], v[96:97] op_sel_hi:[0,1]
	v_pk_fma_f32 v[96:97], v[110:111], v[110:111], v[96:97]
	v_mul_f32_e32 v98, v111, v111
	v_pk_mul_f32 v[82:83], v[82:83], v[150:151] op_sel_hi:[1,0]
	v_pk_add_f32 v[118:119], v[98:99], v[96:97] op_sel_hi:[0,1]
	v_pk_fma_f32 v[96:97], v[66:67], v[148:149], v[82:83] op_sel_hi:[1,0,1]
	v_pk_mul_f32 v[66:67], v[80:81], v[150:151] op_sel_hi:[1,0]
	v_pk_fma_f32 v[98:99], v[64:65], v[148:149], v[66:67] op_sel_hi:[1,0,1]
	v_pk_fma_f32 v[64:65], v[98:99], v[98:99], v[118:119]
	v_mul_f32_e32 v66, v99, v99
	ds_read_b128 v[128:131], v219
	v_pk_add_f32 v[64:65], v[66:67], v[64:65] op_sel_hi:[0,1]
	v_pk_fma_f32 v[64:65], v[96:97], v[96:97], v[64:65]
	v_mul_f32_e32 v66, v97, v97
	v_pk_add_f32 v[64:65], v[66:67], v[64:65] op_sel_hi:[0,1]
	v_pk_mul_f32 v[66:67], v[86:87], v[150:151] op_sel_hi:[1,0]
	v_pk_mul_f32 v[50:51], v[50:51], v[150:151] op_sel_hi:[1,0]
	v_pk_fma_f32 v[80:81], v[70:71], v[148:149], v[66:67] op_sel_hi:[1,0,1]
	v_pk_mul_f32 v[66:67], v[84:85], v[150:151] op_sel_hi:[1,0]
	v_pk_mul_f32 v[18:19], v[18:19], v[150:151] op_sel_hi:[1,0]
	v_pk_fma_f32 v[82:83], v[68:69], v[148:149], v[66:67] op_sel_hi:[1,0,1]
	s_mov_b32 s0, 0x800000
	v_pk_fma_f32 v[64:65], v[82:83], v[82:83], v[64:65]
	v_mul_f32_e32 v66, v83, v83
	v_pk_add_f32 v[64:65], v[66:67], v[64:65] op_sel_hi:[0,1]
	v_pk_fma_f32 v[64:65], v[80:81], v[80:81], v[64:65]
	v_mul_f32_e32 v66, v81, v81
	v_pk_add_f32 v[64:65], v[66:67], v[64:65] op_sel_hi:[0,1]
	v_pk_mul_f32 v[66:67], v[90:91], v[150:151] op_sel_hi:[1,0]
	v_lshl_add_u64 v[140:141], s[68:69], 0, v[140:141]
	v_pk_fma_f32 v[74:75], v[74:75], v[148:149], v[66:67] op_sel_hi:[1,0,1]
	v_pk_mul_f32 v[66:67], v[88:89], v[150:151] op_sel_hi:[1,0]
	v_pk_fma_f32 v[72:73], v[72:73], v[148:149], v[66:67] op_sel_hi:[1,0,1]
	s_lshr_b32 s1, s100, 30
	s_add_i32 s1, s1, 3
	s_cmp_eq_u32 s74, s1
	v_pk_fma_f32 v[64:65], v[72:73], v[72:73], v[64:65]
	v_mul_f32_e32 v66, v73, v73
	v_pk_add_f32 v[64:65], v[66:67], v[64:65] op_sel_hi:[0,1]
	v_pk_fma_f32 v[64:65], v[74:75], v[74:75], v[64:65]
	v_mul_f32_e32 v66, v75, v75
	v_pk_add_f32 v[64:65], v[66:67], v[64:65] op_sel_hi:[0,1]
	v_pk_mul_f32 v[66:67], v[94:95], v[150:151] op_sel_hi:[1,0]
	s_waitcnt vmcnt(16) lgkmcnt(0)
	v_permlane32_swap_b32_e32 v160, v162
	v_permlane32_swap_b32_e32 v161, v163
	v_permlane32_swap_b32_e32 v164, v166
	v_permlane32_swap_b32_e32 v165, v167
	v_permlane32_swap_b32_e32 v168, v170
	v_permlane32_swap_b32_e32 v169, v171
	v_permlane32_swap_b32_e32 v172, v174
	v_permlane32_swap_b32_e32 v173, v175
	v_permlane32_swap_b32_e32 v202, v204
	v_permlane32_swap_b32_e32 v203, v205
	v_permlane32_swap_b32_e32 v244, v246
	v_permlane32_swap_b32_e32 v245, v247
	v_permlane32_swap_b32_e32 v248, v250
	v_permlane32_swap_b32_e32 v249, v251
	v_permlane32_swap_b32_e32 v252, v254
	v_permlane32_swap_b32_e32 v253, v255
	v_lshlrev_b32_e32 v116, 16, v160
	v_pk_fma_f32 v[68:69], v[78:79], v[148:149], v[66:67] op_sel_hi:[1,0,1]
	v_pk_mul_f32 v[66:67], v[92:93], v[150:151] op_sel_hi:[1,0]
	v_and_b32_e32 v117, 0xffff0000, v160
	v_pk_fma_f32 v[70:71], v[76:77], v[148:149], v[66:67] op_sel_hi:[1,0,1]
	s_nop 0
	v_pk_fma_f32 v[64:65], v[70:71], v[70:71], v[64:65]
	v_mul_f32_e32 v66, v71, v71
	v_pk_add_f32 v[64:65], v[66:67], v[64:65] op_sel_hi:[0,1]
	v_pk_fma_f32 v[64:65], v[68:69], v[68:69], v[64:65]
	v_mul_f32_e32 v66, v69, v69
	v_pk_add_f32 v[76:77], v[66:67], v[64:65] op_sel_hi:[0,1]
	v_pk_fma_f32 v[64:65], v[34:35], v[148:149], v[50:51] op_sel_hi:[1,0,1]
	v_pk_mul_f32 v[34:35], v[48:49], v[150:151] op_sel_hi:[1,0]
	s_nop 0
	v_pk_fma_f32 v[66:67], v[32:33], v[148:149], v[34:35] op_sel_hi:[1,0,1]
	s_nop 0
	v_pk_fma_f32 v[32:33], v[66:67], v[66:67], v[76:77]
	v_mul_f32_e32 v34, v67, v67
	v_pk_add_f32 v[32:33], v[34:35], v[32:33] op_sel_hi:[0,1]
	v_pk_fma_f32 v[32:33], v[64:65], v[64:65], v[32:33]
	v_mul_f32_e32 v34, v65, v65
	v_pk_add_f32 v[32:33], v[34:35], v[32:33] op_sel_hi:[0,1]
	v_pk_mul_f32 v[34:35], v[54:55], v[150:151] op_sel_hi:[1,0]
	s_nop 0
	v_pk_fma_f32 v[48:49], v[38:39], v[148:149], v[34:35] op_sel_hi:[1,0,1]
	v_pk_mul_f32 v[34:35], v[52:53], v[150:151] op_sel_hi:[1,0]
	s_nop 0
	v_pk_fma_f32 v[50:51], v[36:37], v[148:149], v[34:35] op_sel_hi:[1,0,1]
	s_nop 0
	v_pk_fma_f32 v[32:33], v[50:51], v[50:51], v[32:33]
	v_mul_f32_e32 v34, v51, v51
	v_pk_add_f32 v[32:33], v[34:35], v[32:33] op_sel_hi:[0,1]
	v_pk_fma_f32 v[32:33], v[48:49], v[48:49], v[32:33]
	v_mul_f32_e32 v34, v49, v49
	v_pk_add_f32 v[32:33], v[34:35], v[32:33] op_sel_hi:[0,1]
	v_pk_mul_f32 v[34:35], v[58:59], v[150:151] op_sel_hi:[1,0]
	s_nop 0
	v_pk_fma_f32 v[42:43], v[42:43], v[148:149], v[34:35] op_sel_hi:[1,0,1]
	v_pk_mul_f32 v[34:35], v[56:57], v[150:151] op_sel_hi:[1,0]
	s_nop 0
	v_pk_fma_f32 v[40:41], v[40:41], v[148:149], v[34:35] op_sel_hi:[1,0,1]
	s_nop 0
	v_pk_fma_f32 v[32:33], v[40:41], v[40:41], v[32:33]
	v_mul_f32_e32 v34, v41, v41
	v_pk_add_f32 v[32:33], v[34:35], v[32:33] op_sel_hi:[0,1]
	v_pk_fma_f32 v[32:33], v[42:43], v[42:43], v[32:33]
	v_mul_f32_e32 v34, v43, v43
	v_pk_add_f32 v[32:33], v[34:35], v[32:33] op_sel_hi:[0,1]
	v_pk_mul_f32 v[34:35], v[62:63], v[150:151] op_sel_hi:[1,0]
	s_nop 0
	v_pk_fma_f32 v[36:37], v[46:47], v[148:149], v[34:35] op_sel_hi:[1,0,1]
	v_pk_mul_f32 v[34:35], v[60:61], v[150:151] op_sel_hi:[1,0]
	s_nop 0
	v_pk_fma_f32 v[38:39], v[44:45], v[148:149], v[34:35] op_sel_hi:[1,0,1]
	s_nop 0
	v_pk_fma_f32 v[32:33], v[38:39], v[38:39], v[32:33]
	v_mul_f32_e32 v34, v39, v39
	v_pk_add_f32 v[32:33], v[34:35], v[32:33] op_sel_hi:[0,1]
	v_pk_fma_f32 v[32:33], v[36:37], v[36:37], v[32:33]
	v_mul_f32_e32 v34, v37, v37
	v_pk_add_f32 v[44:45], v[34:35], v[32:33] op_sel_hi:[0,1]
	v_pk_fma_f32 v[32:33], v[2:3], v[148:149], v[18:19] op_sel_hi:[1,0,1]
	v_pk_mul_f32 v[2:3], v[16:17], v[150:151] op_sel_hi:[1,0]
	s_nop 0
	v_pk_fma_f32 v[34:35], v[0:1], v[148:149], v[2:3] op_sel_hi:[1,0,1]
	s_nop 0
	v_pk_fma_f32 v[0:1], v[34:35], v[34:35], v[44:45]
	v_mul_f32_e32 v2, v35, v35
	v_pk_add_f32 v[0:1], v[2:3], v[0:1] op_sel_hi:[0,1]
	v_pk_fma_f32 v[0:1], v[32:33], v[32:33], v[0:1]
	v_mul_f32_e32 v2, v33, v33
	v_pk_add_f32 v[0:1], v[2:3], v[0:1] op_sel_hi:[0,1]
	v_pk_mul_f32 v[2:3], v[22:23], v[150:151] op_sel_hi:[1,0]
	v_lshlrev_b32_e32 v22, 16, v165
	v_pk_fma_f32 v[16:17], v[6:7], v[148:149], v[2:3] op_sel_hi:[1,0,1]
	v_pk_mul_f32 v[2:3], v[20:21], v[150:151] op_sel_hi:[1,0]
	v_and_b32_e32 v23, 0xffff0000, v165
	v_pk_fma_f32 v[18:19], v[4:5], v[148:149], v[2:3] op_sel_hi:[1,0,1]
	s_nop 0
	v_pk_fma_f32 v[0:1], v[18:19], v[18:19], v[0:1]
	v_mul_f32_e32 v2, v19, v19
	v_pk_add_f32 v[0:1], v[2:3], v[0:1] op_sel_hi:[0,1]
	v_pk_fma_f32 v[0:1], v[16:17], v[16:17], v[0:1]
	v_mul_f32_e32 v2, v17, v17
	v_pk_add_f32 v[0:1], v[2:3], v[0:1] op_sel_hi:[0,1]
	v_pk_mul_f32 v[2:3], v[26:27], v[150:151] op_sel_hi:[1,0]
	s_nop 0
	v_pk_fma_f32 v[10:11], v[10:11], v[148:149], v[2:3] op_sel_hi:[1,0,1]
	v_pk_mul_f32 v[2:3], v[24:25], v[150:151] op_sel_hi:[1,0]
	s_nop 0
	v_pk_fma_f32 v[8:9], v[8:9], v[148:149], v[2:3] op_sel_hi:[1,0,1]
	s_nop 0
	v_pk_fma_f32 v[0:1], v[8:9], v[8:9], v[0:1]
	v_mul_f32_e32 v2, v9, v9
	v_pk_add_f32 v[0:1], v[2:3], v[0:1] op_sel_hi:[0,1]
	v_pk_fma_f32 v[0:1], v[10:11], v[10:11], v[0:1]
	v_mul_f32_e32 v2, v11, v11
	v_pk_add_f32 v[4:5], v[2:3], v[0:1] op_sel_hi:[0,1]
	v_pk_mul_f32 v[2:3], v[28:29], v[150:151] op_sel_hi:[1,0]
	v_pk_mul_f32 v[0:1], v[30:31], v[150:151] op_sel_hi:[1,0]
	v_pk_fma_f32 v[2:3], v[12:13], v[148:149], v[2:3] op_sel_hi:[1,0,1]
	v_pk_fma_f32 v[0:1], v[14:15], v[148:149], v[0:1] op_sel_hi:[1,0,1]
	v_pk_fma_f32 v[4:5], v[2:3], v[2:3], v[4:5]
	v_mul_f32_e32 v6, v3, v3
	v_pk_add_f32 v[4:5], v[6:7], v[4:5] op_sel_hi:[0,1]
	v_pk_fma_f32 v[4:5], v[0:1], v[0:1], v[4:5]
	v_mul_f32_e32 v6, v1, v1
	v_pk_add_f32 v[4:5], v[6:7], v[4:5] op_sel_hi:[0,1]
	v_mov_b32_e32 v5, v4
	s_nop 1
	v_permlane32_swap_b32_e32 v4, v5
	v_add_f32_e32 v4, v4, v5
	v_fmamk_f32 v4, v4, 0x3c000000, v232
	v_mul_f32_e32 v5, 0x4b800000, v4
	v_cmp_gt_f32_e32 vcc, s0, v4
	v_lshlrev_b32_e32 v12, 16, v161
	v_and_b32_e32 v13, 0xffff0000, v161
	v_cndmask_b32_e32 v4, v4, v5, vcc
	v_rsq_f32_e32 v6, v4
	v_lshl_add_u64 v[4:5], v[140:141], 0, v[136:137]
	v_lshlrev_b32_e32 v138, 3, v210
	v_mov_b32_e32 v139, 0
	v_lshl_add_u64 v[142:143], v[138:139], 0, v[4:5]
	v_mul_f32_e32 v7, 0x45800000, v6
	v_cndmask_b32_e32 v6, v6, v7, vcc
	v_mul_f32_e32 v6, 0x3f077f5a, v6
	v_pk_mul_f32 v[14:15], v[112:113], v[6:7] op_sel_hi:[1,0]
	v_pk_mul_f32 v[20:21], v[114:115], v[6:7] op_sel_hi:[1,0]
	v_pk_mul_f32 v[14:15], v[128:129], v[14:15]
	v_pk_mul_f32 v[20:21], v[130:131], v[20:21]
	v_pk_mul_f32 v[14:15], v[14:15], v[116:117]
	v_pk_mul_f32 v[12:13], v[20:21], v[12:13]
	v_cvt_pk_bf16_f32 v144, v14, v15
	v_cvt_pk_bf16_f32 v145, v12, v13
	ds_read_b128 v[12:15], v219 offset:32
	v_pk_mul_f32 v[20:21], v[100:101], v[6:7] op_sel_hi:[1,0]
	v_pk_mul_f32 v[24:25], v[104:105], v[6:7] op_sel_hi:[1,0]
	v_pk_mul_f32 v[26:27], v[106:107], v[6:7] op_sel_hi:[1,0]
	v_pk_mul_f32 v[28:29], v[110:111], v[6:7] op_sel_hi:[1,0]
	v_pk_mul_f32 v[30:31], v[98:99], v[6:7] op_sel_hi:[1,0]
	v_pk_mul_f32 v[44:45], v[96:97], v[6:7] op_sel_hi:[1,0]
	v_pk_mul_f32 v[32:33], v[32:33], v[6:7] op_sel_hi:[1,0]
	v_pk_mul_f32 v[18:19], v[18:19], v[6:7] op_sel_hi:[1,0]
	v_pk_mul_f32 v[16:17], v[16:17], v[6:7] op_sel_hi:[1,0]
	v_pk_mul_f32 v[8:9], v[8:9], v[6:7] op_sel_hi:[1,0]
	v_pk_mul_f32 v[10:11], v[10:11], v[6:7] op_sel_hi:[1,0]
	v_pk_mul_f32 v[2:3], v[2:3], v[6:7] op_sel_hi:[1,0]
	v_pk_mul_f32 v[0:1], v[0:1], v[6:7] op_sel_hi:[1,0]
	s_waitcnt lgkmcnt(0)
	v_pk_mul_f32 v[12:13], v[12:13], v[20:21]
	v_lshlrev_b32_e32 v20, 16, v162
	v_and_b32_e32 v21, 0xffff0000, v162
	v_pk_mul_f32 v[12:13], v[12:13], v[20:21]
	v_pk_mul_f32 v[20:21], v[102:103], v[6:7] op_sel_hi:[1,0]
	v_cvt_pk_bf16_f32 v146, v12, v13
	v_pk_mul_f32 v[14:15], v[14:15], v[20:21]
	v_lshlrev_b32_e32 v20, 16, v163
	v_and_b32_e32 v21, 0xffff0000, v163
	v_pk_mul_f32 v[14:15], v[14:15], v[20:21]
	v_lshlrev_b32_e32 v20, 16, v164
	v_cvt_pk_bf16_f32 v147, v14, v15
	s_nop 1
	v_permlane32_swap_b32_e32 v144, v146
	v_permlane32_swap_b32_e32 v145, v147
	global_store_dwordx4 v[142:143], v[144:147], off
	ds_read_b128 v[12:15], v219 offset:64
	v_and_b32_e32 v21, 0xffff0000, v164
	s_waitcnt lgkmcnt(0)
	v_pk_mul_f32 v[12:13], v[12:13], v[24:25]
	v_pk_mul_f32 v[14:15], v[14:15], v[26:27]
	v_pk_mul_f32 v[12:13], v[12:13], v[20:21]
	v_pk_mul_f32 v[14:15], v[14:15], v[22:23]
	v_cvt_pk_bf16_f32 v144, v12, v13
	v_cvt_pk_bf16_f32 v145, v14, v15
	ds_read_b128 v[12:15], v219 offset:96
	s_nop 0
	v_pk_mul_f32 v[26:27], v[108:109], v[6:7] op_sel_hi:[1,0]
	v_lshlrev_b32_e32 v22, 16, v166
	v_and_b32_e32 v23, 0xffff0000, v166
	v_lshlrev_b32_e32 v24, 16, v167
	v_and_b32_e32 v25, 0xffff0000, v167
	s_waitcnt lgkmcnt(0)
	v_pk_mul_f32 v[12:13], v[12:13], v[26:27]
	v_pk_mul_f32 v[14:15], v[14:15], v[28:29]
	v_pk_mul_f32 v[12:13], v[12:13], v[22:23]
	v_pk_mul_f32 v[14:15], v[14:15], v[24:25]
	v_cvt_pk_bf16_f32 v146, v12, v13
	v_cvt_pk_bf16_f32 v147, v14, v15
	s_nop 1
	v_permlane32_swap_b32_e32 v144, v146
	v_permlane32_swap_b32_e32 v145, v147
	global_store_dwordx4 v[142:143], v[144:147], off offset:32
	ds_read_b128 v[12:15], v219 offset:128
	s_nop 0
	v_lshlrev_b32_e32 v28, 16, v168
	v_and_b32_e32 v29, 0xffff0000, v168
	v_lshlrev_b32_e32 v20, 16, v169
	v_and_b32_e32 v21, 0xffff0000, v169
	s_waitcnt lgkmcnt(0)
	v_pk_mul_f32 v[12:13], v[30:31], v[12:13]
	v_pk_mul_f32 v[14:15], v[44:45], v[14:15]
	v_pk_mul_f32 v[12:13], v[12:13], v[28:29]
	v_pk_mul_f32 v[14:15], v[14:15], v[20:21]
	v_cvt_pk_bf16_f32 v144, v12, v13
	v_cvt_pk_bf16_f32 v145, v14, v15
	ds_read_b128 v[12:15], v219 offset:160
	v_pk_mul_f32 v[28:29], v[82:83], v[6:7] op_sel_hi:[1,0]
	v_pk_mul_f32 v[30:31], v[80:81], v[6:7] op_sel_hi:[1,0]
	v_lshlrev_b32_e32 v20, 16, v170
	v_and_b32_e32 v21, 0xffff0000, v170
	v_lshlrev_b32_e32 v22, 16, v171
	v_and_b32_e32 v23, 0xffff0000, v171
	v_pk_mul_f32 v[44:45], v[64:65], v[6:7] op_sel_hi:[1,0]
	s_waitcnt lgkmcnt(0)
	v_pk_mul_f32 v[12:13], v[28:29], v[12:13]
	v_pk_mul_f32 v[14:15], v[30:31], v[14:15]
	v_pk_mul_f32 v[12:13], v[12:13], v[20:21]
	v_pk_mul_f32 v[14:15], v[14:15], v[22:23]
	v_cvt_pk_bf16_f32 v146, v12, v13
	v_cvt_pk_bf16_f32 v147, v14, v15
	s_nop 1
	v_permlane32_swap_b32_e32 v144, v146
	v_permlane32_swap_b32_e32 v145, v147
	global_store_dwordx4 v[142:143], v[144:147], off offset:64
	ds_read_b128 v[12:15], v219 offset:192
	v_lshlrev_b32_e32 v20, 16, v172
	v_and_b32_e32 v21, 0xffff0000, v172
	v_lshlrev_b32_e32 v22, 16, v173
	v_and_b32_e32 v23, 0xffff0000, v173
	v_pk_mul_f32 v[24:25], v[72:73], v[6:7] op_sel_hi:[1,0]
	v_pk_mul_f32 v[28:29], v[74:75], v[6:7] op_sel_hi:[1,0]
	v_pk_mul_f32 v[30:31], v[66:67], v[6:7] op_sel_hi:[1,0]
	s_waitcnt lgkmcnt(0)
	v_pk_mul_f32 v[12:13], v[24:25], v[12:13]
	v_pk_mul_f32 v[14:15], v[28:29], v[14:15]
	v_pk_mul_f32 v[12:13], v[12:13], v[20:21]
	v_pk_mul_f32 v[14:15], v[14:15], v[22:23]
	v_cvt_pk_bf16_f32 v144, v12, v13
	v_cvt_pk_bf16_f32 v145, v14, v15
	ds_read_b128 v[12:15], v219 offset:224
	s_nop 0
	v_lshlrev_b32_e32 v22, 16, v174
	v_and_b32_e32 v23, 0xffff0000, v174
	v_lshlrev_b32_e32 v24, 16, v175
	v_and_b32_e32 v25, 0xffff0000, v175
	v_pk_mul_f32 v[26:27], v[70:71], v[6:7] op_sel_hi:[1,0]
	v_pk_mul_f32 v[28:29], v[68:69], v[6:7] op_sel_hi:[1,0]
	s_waitcnt lgkmcnt(0)
	v_pk_mul_f32 v[12:13], v[26:27], v[12:13]
	v_pk_mul_f32 v[14:15], v[28:29], v[14:15]
	v_pk_mul_f32 v[12:13], v[12:13], v[22:23]
	v_pk_mul_f32 v[14:15], v[14:15], v[24:25]
	v_cvt_pk_bf16_f32 v146, v12, v13
	v_cvt_pk_bf16_f32 v147, v14, v15
	s_nop 1
	v_permlane32_swap_b32_e32 v144, v146
	v_permlane32_swap_b32_e32 v145, v147
	global_store_dwordx4 v[142:143], v[144:147], off offset:96
	ds_read_b128 v[12:15], v219 offset:256
	s_nop 0
	v_lshlrev_b32_e32 v28, 16, v202
	v_and_b32_e32 v29, 0xffff0000, v202
	v_lshlrev_b32_e32 v20, 16, v203
	v_and_b32_e32 v21, 0xffff0000, v203
	s_waitcnt lgkmcnt(0)
	v_pk_mul_f32 v[12:13], v[30:31], v[12:13]
	v_pk_mul_f32 v[14:15], v[44:45], v[14:15]
	v_pk_mul_f32 v[12:13], v[12:13], v[28:29]
	v_pk_mul_f32 v[14:15], v[14:15], v[20:21]
	v_cvt_pk_bf16_f32 v144, v12, v13
	v_cvt_pk_bf16_f32 v145, v14, v15
	ds_read_b128 v[12:15], v219 offset:288
	v_pk_mul_f32 v[28:29], v[50:51], v[6:7] op_sel_hi:[1,0]
	v_pk_mul_f32 v[30:31], v[48:49], v[6:7] op_sel_hi:[1,0]
	v_lshlrev_b32_e32 v20, 16, v204
	v_and_b32_e32 v21, 0xffff0000, v204
	v_lshlrev_b32_e32 v22, 16, v205
	v_and_b32_e32 v23, 0xffff0000, v205
	s_waitcnt lgkmcnt(0)
	v_pk_mul_f32 v[12:13], v[28:29], v[12:13]
	v_pk_mul_f32 v[14:15], v[30:31], v[14:15]
	v_pk_mul_f32 v[12:13], v[12:13], v[20:21]
	v_pk_mul_f32 v[14:15], v[14:15], v[22:23]
	v_cvt_pk_bf16_f32 v146, v12, v13
	v_cvt_pk_bf16_f32 v147, v14, v15
	s_nop 1
	v_permlane32_swap_b32_e32 v144, v146
	v_permlane32_swap_b32_e32 v145, v147
	global_store_dwordx4 v[142:143], v[144:147], off offset:128
	ds_read_b128 v[12:15], v219 offset:320
	v_lshlrev_b32_e32 v20, 16, v244
	v_and_b32_e32 v21, 0xffff0000, v244
	v_lshlrev_b32_e32 v22, 16, v245
	v_and_b32_e32 v23, 0xffff0000, v245
	v_pk_mul_f32 v[24:25], v[40:41], v[6:7] op_sel_hi:[1,0]
	v_pk_mul_f32 v[28:29], v[42:43], v[6:7] op_sel_hi:[1,0]
	v_pk_mul_f32 v[30:31], v[34:35], v[6:7] op_sel_hi:[1,0]
	s_waitcnt lgkmcnt(0)
	v_pk_mul_f32 v[12:13], v[24:25], v[12:13]
	v_pk_mul_f32 v[14:15], v[28:29], v[14:15]
	v_pk_mul_f32 v[12:13], v[12:13], v[20:21]
	v_pk_mul_f32 v[14:15], v[14:15], v[22:23]
	v_cvt_pk_bf16_f32 v144, v12, v13
	v_cvt_pk_bf16_f32 v145, v14, v15
	ds_read_b128 v[12:15], v219 offset:352
	s_nop 0
	v_lshlrev_b32_e32 v22, 16, v246
	v_and_b32_e32 v23, 0xffff0000, v246
	v_lshlrev_b32_e32 v24, 16, v247
	v_and_b32_e32 v25, 0xffff0000, v247
	v_pk_mul_f32 v[26:27], v[38:39], v[6:7] op_sel_hi:[1,0]
	v_pk_mul_f32 v[28:29], v[36:37], v[6:7] op_sel_hi:[1,0]
	s_waitcnt lgkmcnt(0)
	v_pk_mul_f32 v[12:13], v[26:27], v[12:13]
	v_pk_mul_f32 v[14:15], v[28:29], v[14:15]
	v_pk_mul_f32 v[12:13], v[12:13], v[22:23]
	v_pk_mul_f32 v[14:15], v[14:15], v[24:25]
	v_cvt_pk_bf16_f32 v146, v12, v13
	v_cvt_pk_bf16_f32 v147, v14, v15
	s_nop 1
	v_permlane32_swap_b32_e32 v144, v146
	v_permlane32_swap_b32_e32 v145, v147
	global_store_dwordx4 v[142:143], v[144:147], off offset:160
	ds_read_b128 v[12:15], v219 offset:384
	s_nop 0
	v_lshlrev_b32_e32 v28, 16, v248
	v_and_b32_e32 v29, 0xffff0000, v248
	v_lshlrev_b32_e32 v20, 16, v249
	v_and_b32_e32 v21, 0xffff0000, v249
	s_waitcnt lgkmcnt(0)
	v_pk_mul_f32 v[12:13], v[30:31], v[12:13]
	v_pk_mul_f32 v[14:15], v[32:33], v[14:15]
	v_pk_mul_f32 v[12:13], v[12:13], v[28:29]
	v_pk_mul_f32 v[14:15], v[14:15], v[20:21]
	v_cvt_pk_bf16_f32 v144, v12, v13
	v_cvt_pk_bf16_f32 v145, v14, v15
	ds_read_b128 v[12:15], v219 offset:416
	v_lshlrev_b32_e32 v20, 16, v250
	v_and_b32_e32 v21, 0xffff0000, v250
	v_lshlrev_b32_e32 v22, 16, v251
	v_and_b32_e32 v23, 0xffff0000, v251
	s_waitcnt lgkmcnt(0)
	v_pk_mul_f32 v[12:13], v[18:19], v[12:13]
	v_pk_mul_f32 v[14:15], v[16:17], v[14:15]
	v_pk_mul_f32 v[12:13], v[12:13], v[20:21]
	v_pk_mul_f32 v[14:15], v[14:15], v[22:23]
	v_cvt_pk_bf16_f32 v146, v12, v13
	v_cvt_pk_bf16_f32 v147, v14, v15
	s_nop 1
	v_permlane32_swap_b32_e32 v144, v146
	v_permlane32_swap_b32_e32 v145, v147
	global_store_dwordx4 v[142:143], v[144:147], off offset:192
	ds_read_b128 v[12:15], v219 offset:448
	v_lshlrev_b32_e32 v16, 16, v252
	v_and_b32_e32 v17, 0xffff0000, v252
	v_lshlrev_b32_e32 v18, 16, v253
	v_and_b32_e32 v19, 0xffff0000, v253
	s_waitcnt lgkmcnt(0)
	v_pk_mul_f32 v[8:9], v[8:9], v[12:13]
	v_pk_mul_f32 v[10:11], v[10:11], v[14:15]
	v_pk_mul_f32 v[8:9], v[8:9], v[16:17]
	v_pk_mul_f32 v[10:11], v[10:11], v[18:19]
	v_cvt_pk_bf16_f32 v144, v8, v9
	v_cvt_pk_bf16_f32 v145, v10, v11
	ds_read_b128 v[8:11], v219 offset:480
	v_lshlrev_b32_e32 v12, 16, v254
	v_and_b32_e32 v13, 0xffff0000, v254
	v_lshlrev_b32_e32 v14, 16, v255
	v_and_b32_e32 v15, 0xffff0000, v255
	s_waitcnt lgkmcnt(0)
	v_pk_mul_f32 v[2:3], v[2:3], v[8:9]
	v_pk_mul_f32 v[0:1], v[0:1], v[10:11]
	v_pk_mul_f32 v[2:3], v[2:3], v[12:13]
	v_pk_mul_f32 v[0:1], v[0:1], v[14:15]
	v_cvt_pk_bf16_f32 v146, v2, v3
	v_cvt_pk_bf16_f32 v147, v0, v1
	s_nop 1
	v_permlane32_swap_b32_e32 v144, v146
	v_permlane32_swap_b32_e32 v145, v147
	global_store_dwordx4 v[142:143], v[144:147], off offset:224
	s_cbranch_scc1 .LBB0_735
	s_branch .LBB0_736
